# P0 forget-gate log-sigmoid: libm expf/log1pf/sqrt/div sequence (190 instr per row) replaced by v_rsq/v_exp/v_log f32 hardware transcendentals
# baseline (speedup 1.0000x reference)
; __global__ void __launch_bounds__(NTHR, 2) hybrid_fwd(Args args) {
;     ...
;                 const float rs = 1.0f / sqrtf(s * (1.0f / DM) + EPS);
;                 if (lane == 0) SSQ0[row] = s;
;                 if ((lane & 7) == 0) { const int h = lane >> 3; const float z = d[0] * rs + b_forget[h]; const float lsv = fminf(z, 0.f) - log1pf(expf(-fabsf(z)));
;                     const int bb = row >> 11, sp = row & 2047; __hip_atomic_store(LS + ((size_t)bb * 8 + h) * SEQ + sp, lsv, __ATOMIC_RELAXED, __HIP_MEMORY_SCOPE_AGENT); }
.LBB0_198:
	s_or_b64 exec, exec, s[14:15]
	s_and_saveexec_b64 s[44:45], s[6:7]
	s_cbranch_execz .LBB0_193
	global_load_dword v19, v[40:41], off
	v_fmamk_f32 v18, v18, 0x3a800000, v51
	v_rsq_f32_e32 v20, v18
	s_waitcnt lgkmcnt(0)
	v_add_f32_e32 v16, v16, v17
	s_and_b32 s27, s34, 0x7ff
	s_ashr_i32 s14, s34, 11
	s_ashr_i32 s15, s14, 31
	s_lshl_b64 s[14:15], s[14:15], 16
	s_lshl_b32 s34, s27, 2
	s_waitcnt vmcnt(0)
	v_fmac_f32_e32 v19, v20, v16
	v_mul_f32_e64 v16, |v19|, s46
	v_min_f32_e32 v30, 0, v19
	v_exp_f32_e32 v16, v16
	s_nop 0
	v_add_f32_e32 v16, 1.0, v16
	v_log_f32_e32 v16, v16
	s_nop 0
	v_mul_f32_e32 v16, 0x3f317218, v16
	v_sub_f32_e32 v18, v30, v16
	v_lshl_add_u64 v[16:17], v[42:43], 0, s[14:15]
	v_lshl_add_u64 v[16:17], v[16:17], 0, s[34:35]
	global_store_dword v[16:17], v18, off sc1
	s_branch .LBB0_193
